# skinny remainders of the N=4096 and N=2816 phases: the unit's weight slice is fetched once per workgroup (four k-steps per wave) and shared through LDS instead of being fetched by all eight waves
# speedup vs baseline: 1.0012x; 1.0012x over previous
.LBB0_339:
	v_add_co_u32_e32 v56, vcc, 0x100000, v16
	s_nop 1
	v_addc_co_u32_e32 v57, vcc, 0, v17, vcc
	v_add_co_u32_e32 v58, vcc, 0xbc11000, v14
	s_nop 1
	v_addc_co_u32_e32 v59, vcc, 0, v15, vcc
	s_barrier
	v_lshlrev_b32_e32 v172, 4, v146
	s_lshl_b32 s22, s36, 12
	v_add_u32_e32 v173, s22, v172
	s_lshl_b32 s22, s36, 8
	v_add_co_u32_e32 v174, vcc, s22, v56
	s_nop 1
	v_addc_co_u32_e32 v175, vcc, 0, v57, vcc
	global_load_dwordx4 v[132:135], v[174:175], off
	global_load_dwordx4 v[136:139], v[174:175], off offset:64
	global_load_dwordx4 v[140:143], v[174:175], off offset:128
	global_load_dwordx4 v[148:151], v[174:175], off offset:192
	global_load_dwordx4 v[176:179], v[58:59], off
	global_load_dwordx4 v[180:183], v[58:59], off offset:64
	global_load_dwordx4 v[184:187], v[58:59], off offset:128
	global_load_dwordx4 v[188:191], v[58:59], off offset:192
	global_load_dwordx4 v[192:195], v[58:59], off offset:256
	global_load_dwordx4 v[196:199], v[58:59], off offset:320
	global_load_dwordx4 v[200:203], v[58:59], off offset:384
	global_load_dwordx4 v[204:207], v[58:59], off offset:448
	global_load_dwordx4 v[208:211], v[58:59], off offset:512
	global_load_dwordx4 v[212:215], v[58:59], off offset:576
	global_load_dwordx4 v[216:219], v[58:59], off offset:640
	global_load_dwordx4 v[220:223], v[58:59], off offset:704
	global_load_dwordx4 v[224:227], v[58:59], off offset:768
	global_load_dwordx4 v[228:231], v[58:59], off offset:832
	global_load_dwordx4 v[232:235], v[58:59], off offset:896
	global_load_dwordx4 v[236:239], v[58:59], off offset:960
	global_load_dwordx4 v[24:27], v[58:59], off offset:1024
	global_load_dwordx4 v[28:31], v[58:59], off offset:1088
	global_load_dwordx4 v[32:35], v[58:59], off offset:1152
	global_load_dwordx4 v[36:39], v[58:59], off offset:1216
	global_load_dwordx4 v[40:43], v[58:59], off offset:1280
	global_load_dwordx4 v[44:47], v[58:59], off offset:1344
	global_load_dwordx4 v[48:51], v[58:59], off offset:1408
	global_load_dwordx4 v[52:55], v[58:59], off offset:1472
	s_waitcnt vmcnt(27)
	ds_write_b128 v173, v[132:135]
	s_waitcnt vmcnt(26)
	ds_write_b128 v173, v[136:139] offset:1024
	s_waitcnt vmcnt(25)
	ds_write_b128 v173, v[140:143] offset:2048
	s_waitcnt vmcnt(24)
	ds_write_b128 v173, v[148:151] offset:3072
	global_load_dwordx4 v[132:135], v[58:59], off offset:1536
	global_load_dwordx4 v[136:139], v[58:59], off offset:1600
	global_load_dwordx4 v[140:143], v[58:59], off offset:1664
	global_load_dwordx4 v[148:151], v[58:59], off offset:1728
	s_waitcnt lgkmcnt(0)
	s_barrier
	ds_read_b128 v[152:155], v172
	ds_read_b128 v[156:159], v172 offset:1024
	s_waitcnt vmcnt(27) lgkmcnt(1)
	v_mfma_f32_16x16x32_bf16 v[2:5], v[152:155], v[176:179], v[2:5]
	global_load_dwordx4 v[176:179], v[58:59], off offset:1792
	ds_read_b128 v[168:171], v172 offset:2048
	s_waitcnt vmcnt(27) lgkmcnt(1)
	v_mfma_f32_16x16x32_bf16 v[2:5], v[156:159], v[180:183], v[2:5]
	global_load_dwordx4 v[180:183], v[58:59], off offset:1856
	ds_read_b128 v[152:155], v172 offset:3072
	s_waitcnt vmcnt(27) lgkmcnt(1)
	v_mfma_f32_16x16x32_bf16 v[2:5], v[168:171], v[184:187], v[2:5]
	global_load_dwordx4 v[184:187], v[58:59], off offset:1920
	ds_read_b128 v[156:159], v172 offset:4096
	s_waitcnt vmcnt(27) lgkmcnt(1)
	v_mfma_f32_16x16x32_bf16 v[2:5], v[152:155], v[188:191], v[2:5]
	global_load_dwordx4 v[188:191], v[58:59], off offset:1984
	ds_read_b128 v[168:171], v172 offset:5120
	s_waitcnt vmcnt(27) lgkmcnt(1)
	v_mfma_f32_16x16x32_bf16 v[2:5], v[156:159], v[192:195], v[2:5]
	ds_read_b128 v[152:155], v172 offset:6144
	s_waitcnt vmcnt(26) lgkmcnt(1)
	v_mfma_f32_16x16x32_bf16 v[2:5], v[168:171], v[196:199], v[2:5]
	ds_read_b128 v[156:159], v172 offset:7168
	s_waitcnt vmcnt(25) lgkmcnt(1)
	v_mfma_f32_16x16x32_bf16 v[2:5], v[152:155], v[200:203], v[2:5]
	ds_read_b128 v[168:171], v172 offset:8192
	s_waitcnt vmcnt(24) lgkmcnt(1)
	v_mfma_f32_16x16x32_bf16 v[2:5], v[156:159], v[204:207], v[2:5]
	ds_read_b128 v[152:155], v172 offset:9216
	s_waitcnt vmcnt(23) lgkmcnt(1)
	v_mfma_f32_16x16x32_bf16 v[2:5], v[168:171], v[208:211], v[2:5]
	ds_read_b128 v[156:159], v172 offset:10240
	s_waitcnt vmcnt(22) lgkmcnt(1)
	v_mfma_f32_16x16x32_bf16 v[2:5], v[152:155], v[212:215], v[2:5]
	ds_read_b128 v[168:171], v172 offset:11264
	s_waitcnt vmcnt(21) lgkmcnt(1)
	v_mfma_f32_16x16x32_bf16 v[2:5], v[156:159], v[216:219], v[2:5]
	ds_read_b128 v[152:155], v172 offset:12288
	s_waitcnt vmcnt(20) lgkmcnt(1)
	v_mfma_f32_16x16x32_bf16 v[2:5], v[168:171], v[220:223], v[2:5]
	ds_read_b128 v[156:159], v172 offset:13312
	s_waitcnt vmcnt(19) lgkmcnt(1)
	v_mfma_f32_16x16x32_bf16 v[2:5], v[152:155], v[224:227], v[2:5]
	ds_read_b128 v[168:171], v172 offset:14336
	s_waitcnt vmcnt(18) lgkmcnt(1)
	v_mfma_f32_16x16x32_bf16 v[2:5], v[156:159], v[228:231], v[2:5]
	ds_read_b128 v[152:155], v172 offset:15360
	s_waitcnt vmcnt(17) lgkmcnt(1)
	v_mfma_f32_16x16x32_bf16 v[2:5], v[168:171], v[232:235], v[2:5]
	ds_read_b128 v[156:159], v172 offset:16384
	s_waitcnt vmcnt(16) lgkmcnt(1)
	v_mfma_f32_16x16x32_bf16 v[2:5], v[152:155], v[236:239], v[2:5]
	ds_read_b128 v[168:171], v172 offset:17408
	s_waitcnt vmcnt(15) lgkmcnt(1)
	v_mfma_f32_16x16x32_bf16 v[2:5], v[156:159], v[24:27], v[2:5]
	ds_read_b128 v[152:155], v172 offset:18432
	s_waitcnt vmcnt(14) lgkmcnt(1)
	v_mfma_f32_16x16x32_bf16 v[2:5], v[168:171], v[28:31], v[2:5]
	ds_read_b128 v[156:159], v172 offset:19456
	s_waitcnt vmcnt(13) lgkmcnt(1)
	v_mfma_f32_16x16x32_bf16 v[2:5], v[152:155], v[32:35], v[2:5]
	ds_read_b128 v[168:171], v172 offset:20480
	s_waitcnt vmcnt(12) lgkmcnt(1)
	v_mfma_f32_16x16x32_bf16 v[2:5], v[156:159], v[36:39], v[2:5]
	ds_read_b128 v[152:155], v172 offset:21504
	s_waitcnt vmcnt(11) lgkmcnt(1)
	v_mfma_f32_16x16x32_bf16 v[2:5], v[168:171], v[40:43], v[2:5]
	ds_read_b128 v[156:159], v172 offset:22528
	s_waitcnt vmcnt(10) lgkmcnt(1)
	v_mfma_f32_16x16x32_bf16 v[2:5], v[152:155], v[44:47], v[2:5]
	ds_read_b128 v[168:171], v172 offset:23552
	s_waitcnt vmcnt(9) lgkmcnt(1)
	v_mfma_f32_16x16x32_bf16 v[2:5], v[156:159], v[48:51], v[2:5]
	ds_read_b128 v[152:155], v172 offset:24576
	s_waitcnt vmcnt(8) lgkmcnt(1)
	v_mfma_f32_16x16x32_bf16 v[2:5], v[168:171], v[52:55], v[2:5]
	ds_read_b128 v[156:159], v172 offset:25600
	s_waitcnt vmcnt(7) lgkmcnt(1)
	v_mfma_f32_16x16x32_bf16 v[2:5], v[152:155], v[132:135], v[2:5]
	ds_read_b128 v[168:171], v172 offset:26624
	s_waitcnt vmcnt(6) lgkmcnt(1)
	v_mfma_f32_16x16x32_bf16 v[2:5], v[156:159], v[136:139], v[2:5]
	ds_read_b128 v[152:155], v172 offset:27648
	s_waitcnt vmcnt(5) lgkmcnt(1)
	v_mfma_f32_16x16x32_bf16 v[2:5], v[168:171], v[140:143], v[2:5]
	ds_read_b128 v[156:159], v172 offset:28672
	s_waitcnt vmcnt(4) lgkmcnt(1)
	v_mfma_f32_16x16x32_bf16 v[2:5], v[152:155], v[148:151], v[2:5]
	ds_read_b128 v[168:171], v172 offset:29696
	s_waitcnt vmcnt(3) lgkmcnt(1)
	v_mfma_f32_16x16x32_bf16 v[2:5], v[156:159], v[176:179], v[2:5]
	ds_read_b128 v[152:155], v172 offset:30720
	s_waitcnt vmcnt(2) lgkmcnt(1)
	v_mfma_f32_16x16x32_bf16 v[2:5], v[168:171], v[180:183], v[2:5]
	ds_read_b128 v[156:159], v172 offset:31744
	s_waitcnt vmcnt(1) lgkmcnt(1)
	v_mfma_f32_16x16x32_bf16 v[2:5], v[152:155], v[184:187], v[2:5]
	s_waitcnt vmcnt(0) lgkmcnt(0)
	v_mfma_f32_16x16x32_bf16 v[2:5], v[156:159], v[188:191], v[2:5]
	s_movk_i32 s4, 0x800
	s_nop 1
	v_lshl_or_b32 v16, s8, 4, v18
	v_ashrrev_i32_e32 v17, 31, v16
	s_add_i32 s8, s8, s90
	s_nop 3
	v_cvt_pk_bf16_f32 v2, v2, v3
	v_cvt_pk_bf16_f32 v3, v4, v5
	v_lshl_add_u64 v[4:5], v[16:17], 1, v[8:9]
	s_cmpk_gt_i32 s8, 0xff
	v_add_u32_e32 v12, s3, v12
	global_store_dwordx2 v[4:5], v[2:3], off
	s_cbranch_scc0 .LBB0_338

.LBB0_1464:
	v_add_co_u32_e32 v58, vcc, 0xb00000, v18
	s_nop 1
	v_addc_co_u32_e32 v59, vcc, 0, v19, vcc
	v_add_co_u32_e32 v60, vcc, 0xbc11000, v16
	s_nop 1
	v_addc_co_u32_e32 v61, vcc, 0, v17, vcc
	s_barrier
	v_lshlrev_b32_e32 v172, 4, v146
	s_lshl_b32 s22, s36, 12
	v_add_u32_e32 v173, s22, v172
	s_lshl_b32 s22, s36, 8
	v_add_co_u32_e32 v174, vcc, s22, v58
	s_nop 1
	v_addc_co_u32_e32 v175, vcc, 0, v59, vcc
	global_load_dwordx4 v[132:135], v[174:175], off
	global_load_dwordx4 v[136:139], v[174:175], off offset:64
	global_load_dwordx4 v[140:143], v[174:175], off offset:128
	global_load_dwordx4 v[148:151], v[174:175], off offset:192
	global_load_dwordx4 v[176:179], v[60:61], off
	global_load_dwordx4 v[180:183], v[60:61], off offset:64
	global_load_dwordx4 v[184:187], v[60:61], off offset:128
	global_load_dwordx4 v[188:191], v[60:61], off offset:192
	global_load_dwordx4 v[192:195], v[60:61], off offset:256
	global_load_dwordx4 v[196:199], v[60:61], off offset:320
	global_load_dwordx4 v[200:203], v[60:61], off offset:384
	global_load_dwordx4 v[204:207], v[60:61], off offset:448
	global_load_dwordx4 v[208:211], v[60:61], off offset:512
	global_load_dwordx4 v[212:215], v[60:61], off offset:576
	global_load_dwordx4 v[216:219], v[60:61], off offset:640
	global_load_dwordx4 v[220:223], v[60:61], off offset:704
	global_load_dwordx4 v[224:227], v[60:61], off offset:768
	global_load_dwordx4 v[228:231], v[60:61], off offset:832
	global_load_dwordx4 v[232:235], v[60:61], off offset:896
	global_load_dwordx4 v[236:239], v[60:61], off offset:960
	global_load_dwordx4 v[26:29], v[60:61], off offset:1024
	global_load_dwordx4 v[30:33], v[60:61], off offset:1088
	global_load_dwordx4 v[34:37], v[60:61], off offset:1152
	global_load_dwordx4 v[38:41], v[60:61], off offset:1216
	global_load_dwordx4 v[42:45], v[60:61], off offset:1280
	global_load_dwordx4 v[46:49], v[60:61], off offset:1344
	global_load_dwordx4 v[50:53], v[60:61], off offset:1408
	global_load_dwordx4 v[54:57], v[60:61], off offset:1472
	s_waitcnt vmcnt(27)
	ds_write_b128 v173, v[132:135]
	s_waitcnt vmcnt(26)
	ds_write_b128 v173, v[136:139] offset:1024
	s_waitcnt vmcnt(25)
	ds_write_b128 v173, v[140:143] offset:2048
	s_waitcnt vmcnt(24)
	ds_write_b128 v173, v[148:151] offset:3072
	global_load_dwordx4 v[132:135], v[60:61], off offset:1536
	global_load_dwordx4 v[136:139], v[60:61], off offset:1600
	global_load_dwordx4 v[140:143], v[60:61], off offset:1664
	global_load_dwordx4 v[148:151], v[60:61], off offset:1728
	s_waitcnt lgkmcnt(0)
	s_barrier
	ds_read_b128 v[152:155], v172
	ds_read_b128 v[156:159], v172 offset:1024
	s_waitcnt vmcnt(27) lgkmcnt(1)
	v_mfma_f32_16x16x32_bf16 v[2:5], v[152:155], v[176:179], v[2:5]
	global_load_dwordx4 v[176:179], v[60:61], off offset:1792
	ds_read_b128 v[168:171], v172 offset:2048
	s_waitcnt vmcnt(27) lgkmcnt(1)
	v_mfma_f32_16x16x32_bf16 v[2:5], v[156:159], v[180:183], v[2:5]
	global_load_dwordx4 v[180:183], v[60:61], off offset:1856
	ds_read_b128 v[152:155], v172 offset:3072
	s_waitcnt vmcnt(27) lgkmcnt(1)
	v_mfma_f32_16x16x32_bf16 v[2:5], v[168:171], v[184:187], v[2:5]
	global_load_dwordx4 v[184:187], v[60:61], off offset:1920
	ds_read_b128 v[156:159], v172 offset:4096
	s_waitcnt vmcnt(27) lgkmcnt(1)
	v_mfma_f32_16x16x32_bf16 v[2:5], v[152:155], v[188:191], v[2:5]
	global_load_dwordx4 v[188:191], v[60:61], off offset:1984
	ds_read_b128 v[168:171], v172 offset:5120
	s_waitcnt vmcnt(27) lgkmcnt(1)
	v_mfma_f32_16x16x32_bf16 v[2:5], v[156:159], v[192:195], v[2:5]
	ds_read_b128 v[152:155], v172 offset:6144
	s_waitcnt vmcnt(26) lgkmcnt(1)
	v_mfma_f32_16x16x32_bf16 v[2:5], v[168:171], v[196:199], v[2:5]
	ds_read_b128 v[156:159], v172 offset:7168
	s_waitcnt vmcnt(25) lgkmcnt(1)
	v_mfma_f32_16x16x32_bf16 v[2:5], v[152:155], v[200:203], v[2:5]
	ds_read_b128 v[168:171], v172 offset:8192
	s_waitcnt vmcnt(24) lgkmcnt(1)
	v_mfma_f32_16x16x32_bf16 v[2:5], v[156:159], v[204:207], v[2:5]
	ds_read_b128 v[152:155], v172 offset:9216
	s_waitcnt vmcnt(23) lgkmcnt(1)
	v_mfma_f32_16x16x32_bf16 v[2:5], v[168:171], v[208:211], v[2:5]
	ds_read_b128 v[156:159], v172 offset:10240
	s_waitcnt vmcnt(22) lgkmcnt(1)
	v_mfma_f32_16x16x32_bf16 v[2:5], v[152:155], v[212:215], v[2:5]
	ds_read_b128 v[168:171], v172 offset:11264
	s_waitcnt vmcnt(21) lgkmcnt(1)
	v_mfma_f32_16x16x32_bf16 v[2:5], v[156:159], v[216:219], v[2:5]
	ds_read_b128 v[152:155], v172 offset:12288
	s_waitcnt vmcnt(20) lgkmcnt(1)
	v_mfma_f32_16x16x32_bf16 v[2:5], v[168:171], v[220:223], v[2:5]
	ds_read_b128 v[156:159], v172 offset:13312
	s_waitcnt vmcnt(19) lgkmcnt(1)
	v_mfma_f32_16x16x32_bf16 v[2:5], v[152:155], v[224:227], v[2:5]
	ds_read_b128 v[168:171], v172 offset:14336
	s_waitcnt vmcnt(18) lgkmcnt(1)
	v_mfma_f32_16x16x32_bf16 v[2:5], v[156:159], v[228:231], v[2:5]
	ds_read_b128 v[152:155], v172 offset:15360
	s_waitcnt vmcnt(17) lgkmcnt(1)
	v_mfma_f32_16x16x32_bf16 v[2:5], v[168:171], v[232:235], v[2:5]
	ds_read_b128 v[156:159], v172 offset:16384
	s_waitcnt vmcnt(16) lgkmcnt(1)
	v_mfma_f32_16x16x32_bf16 v[2:5], v[152:155], v[236:239], v[2:5]
	ds_read_b128 v[168:171], v172 offset:17408
	s_waitcnt vmcnt(15) lgkmcnt(1)
	v_mfma_f32_16x16x32_bf16 v[2:5], v[156:159], v[26:29], v[2:5]
	ds_read_b128 v[152:155], v172 offset:18432
	s_waitcnt vmcnt(14) lgkmcnt(1)
	v_mfma_f32_16x16x32_bf16 v[2:5], v[168:171], v[30:33], v[2:5]
	ds_read_b128 v[156:159], v172 offset:19456
	s_waitcnt vmcnt(13) lgkmcnt(1)
	v_mfma_f32_16x16x32_bf16 v[2:5], v[152:155], v[34:37], v[2:5]
	ds_read_b128 v[168:171], v172 offset:20480
	s_waitcnt vmcnt(12) lgkmcnt(1)
	v_mfma_f32_16x16x32_bf16 v[2:5], v[156:159], v[38:41], v[2:5]
	ds_read_b128 v[152:155], v172 offset:21504
	s_waitcnt vmcnt(11) lgkmcnt(1)
	v_mfma_f32_16x16x32_bf16 v[2:5], v[168:171], v[42:45], v[2:5]
	ds_read_b128 v[156:159], v172 offset:22528
	s_waitcnt vmcnt(10) lgkmcnt(1)
	v_mfma_f32_16x16x32_bf16 v[2:5], v[152:155], v[46:49], v[2:5]
	ds_read_b128 v[168:171], v172 offset:23552
	s_waitcnt vmcnt(9) lgkmcnt(1)
	v_mfma_f32_16x16x32_bf16 v[2:5], v[156:159], v[50:53], v[2:5]
	ds_read_b128 v[152:155], v172 offset:24576
	s_waitcnt vmcnt(8) lgkmcnt(1)
	v_mfma_f32_16x16x32_bf16 v[2:5], v[168:171], v[54:57], v[2:5]
	ds_read_b128 v[156:159], v172 offset:25600
	s_waitcnt vmcnt(7) lgkmcnt(1)
	v_mfma_f32_16x16x32_bf16 v[2:5], v[152:155], v[132:135], v[2:5]
	ds_read_b128 v[168:171], v172 offset:26624
	s_waitcnt vmcnt(6) lgkmcnt(1)
	v_mfma_f32_16x16x32_bf16 v[2:5], v[156:159], v[136:139], v[2:5]
	ds_read_b128 v[152:155], v172 offset:27648
	s_waitcnt vmcnt(5) lgkmcnt(1)
	v_mfma_f32_16x16x32_bf16 v[2:5], v[168:171], v[140:143], v[2:5]
	ds_read_b128 v[156:159], v172 offset:28672
	s_waitcnt vmcnt(4) lgkmcnt(1)
	v_mfma_f32_16x16x32_bf16 v[2:5], v[152:155], v[148:151], v[2:5]
	ds_read_b128 v[168:171], v172 offset:29696
	s_waitcnt vmcnt(3) lgkmcnt(1)
	v_mfma_f32_16x16x32_bf16 v[2:5], v[156:159], v[176:179], v[2:5]
	ds_read_b128 v[152:155], v172 offset:30720
	s_waitcnt vmcnt(2) lgkmcnt(1)
	v_mfma_f32_16x16x32_bf16 v[2:5], v[168:171], v[180:183], v[2:5]
	ds_read_b128 v[156:159], v172 offset:31744
	s_waitcnt vmcnt(1) lgkmcnt(1)
	v_mfma_f32_16x16x32_bf16 v[2:5], v[152:155], v[184:187], v[2:5]
	s_waitcnt vmcnt(0) lgkmcnt(0)
	v_mfma_f32_16x16x32_bf16 v[2:5], v[156:159], v[188:191], v[2:5]
	s_movk_i32 s4, 0x800
	s_nop 1
	v_lshl_or_b32 v18, s7, 4, v20
	v_cmp_gt_i32_e32 vcc, s6, v18
	s_and_saveexec_b64 s[4:5], vcc
	s_cbranch_execz .LBB0_1462
	global_load_dwordx4 v[22:25], v[8:9], off
	global_load_dwordx4 v[26:29], v[8:9], off offset:16
	v_ashrrev_i32_e32 v19, 31, v18
	s_waitcnt vmcnt(1)
	v_mov_b32_e32 v30, v22
	s_waitcnt vmcnt(0)
	v_mov_b32_e32 v31, v26
	v_mov_b32_e32 v26, v23
	v_mov_b32_e32 v22, v24
	v_mov_b32_e32 v23, v28
	v_mov_b32_e32 v28, v25
	v_pk_add_f32 v[24:25], v[30:31], v[26:27]
	v_pk_add_f32 v[22:23], v[22:23], v[28:29]
	s_nop 0
	v_pk_add_f32 v[22:23], v[24:25], v[22:23]
	s_nop 0
	v_add_f32_e32 v6, v22, v23
	v_fmamk_f32 v6, v6, 0x3a800000, v1
	v_rsq_f32_e32 v6, v6
	s_nop 0
	v_pk_mul_f32 v[4:5], v[4:5], v[6:7] op_sel_hi:[1,0]
	v_pk_mul_f32 v[2:3], v[2:3], v[6:7] op_sel_hi:[1,0]
	s_nop 0
	v_cvt_pk_bf16_f32 v2, v2, v3
	v_cvt_pk_bf16_f32 v3, v4, v5
	v_lshl_add_u64 v[4:5], v[18:19], 1, v[10:11]
	global_store_dwordx2 v[4:5], v[2:3], off
	s_branch .LBB0_1462
